# selective nt v2: second-of-pair units keep only the band rows reused by the next row chunk at default policy
# baseline (speedup 1.0000x reference)
; template <int KIND> __device__ __forceinline__ void attn_dma(unsigned dst, const bf16_t* src, const AttnUnit& u, int wid, int lane) {
;     const int np = u.nrows * 5;
;     const char* base = (const char*)(src + ((size_t)(u.b * NHEAD + u.h) * SEQ + u.krow_lo * 64 + 24 * u.jh) * HD);
; #pragma unroll
;     for (int it = 0; it < 10; ++it) {
;         const int pi = it * 8 + wid;
;         if (pi < np) {
;             const int w = (pi * 205) >> 10, p = pi - 5 * w, c = 8 * p + (lane >> 3);
;             const int sw = (KIND == 0) ? (((c >> 1) & 1) | (((c >> 3) & 3) << 1)) : ((((c >> 1) & 1) << 1) | (((c >> 3) & 1) << 2));
;             const int ch = (lane & 7) ^ sw;
;             const char* gp = base + (w * 64 + c) * (HD * 2) + ch * 16;
;             glds16(gp, (unsigned)__builtin_amdgcn_readfirstlane(dst + pi * 1024));
;         }
;     }
; }
.LBB0_263:
	s_cmp_eq_u32 s98, 2
	s_cbranch_scc1 .LBB0_336
	s_cmpk_gt_i32 s86, 0xff
	s_cbranch_scc1 .LBB0_336
	s_mov_b32 s100, 0
	s_cmp_ge_u32 s85, 5
	s_cselect_b32 s1, 5, 0
	s_sub_i32 s0, s85, s1
	s_cmp_ge_u32 s0, 3
	s_cselect_b32 s1, 0x1, 0
	s_or_b32 s100, s100, s1
	s_cmp_le_u32 s0, 1
	s_cselect_b32 s1, 0x0, 0
	s_or_b32 s100, s100, s1
	s_add_i32 s0, s0, 3
	s_cmp_ge_u32 s0, 5
	s_cselect_b32 s1, 5, 0
	s_sub_i32 s0, s0, s1
	s_cmp_ge_u32 s0, 3
	s_cselect_b32 s1, 0x2, 0
	s_or_b32 s100, s100, s1
	s_cmp_le_u32 s0, 1
	s_cselect_b32 s1, 0x0, 0
	s_or_b32 s100, s100, s1
	s_add_i32 s0, s0, 3
	s_cmp_ge_u32 s0, 5
	s_cselect_b32 s1, 5, 0
	s_sub_i32 s0, s0, s1
	s_cmp_ge_u32 s0, 3
	s_cselect_b32 s1, 0x4, 0
	s_or_b32 s100, s100, s1
	s_cmp_le_u32 s0, 1
	s_cselect_b32 s1, 0x0, 0
	s_or_b32 s100, s100, s1
	s_add_i32 s0, s0, 3
	s_cmp_ge_u32 s0, 5
	s_cselect_b32 s1, 5, 0
	s_sub_i32 s0, s0, s1
	s_cmp_ge_u32 s0, 3
	s_cselect_b32 s1, 0x8, 0
	s_or_b32 s100, s100, s1
	s_cmp_le_u32 s0, 1
	s_cselect_b32 s1, 0x0, 0
	s_or_b32 s100, s100, s1
	s_add_i32 s0, s0, 3
	s_cmp_ge_u32 s0, 5
	s_cselect_b32 s1, 5, 0
	s_sub_i32 s0, s0, s1
	s_cmp_ge_u32 s0, 3
	s_cselect_b32 s1, 0x10, 0
	s_or_b32 s100, s100, s1
	s_cmp_le_u32 s0, 1
	s_cselect_b32 s1, 0x0, 0
	s_or_b32 s100, s100, s1
	s_add_i32 s0, s0, 3
	s_cmp_ge_u32 s0, 5
	s_cselect_b32 s1, 5, 0
	s_sub_i32 s0, s0, s1
	s_cmp_ge_u32 s0, 3
	s_cselect_b32 s1, 0x20, 0
	s_or_b32 s100, s100, s1
	s_cmp_le_u32 s0, 1
	s_cselect_b32 s1, 0x200000, 0
	s_or_b32 s100, s100, s1
	s_add_i32 s0, s0, 3
	s_cmp_ge_u32 s0, 5
	s_cselect_b32 s1, 5, 0
	s_sub_i32 s0, s0, s1
	s_cmp_ge_u32 s0, 3
	s_cselect_b32 s1, 0x40, 0
	s_or_b32 s100, s100, s1
	s_cmp_le_u32 s0, 1
	s_cselect_b32 s1, 0x400000, 0
	s_or_b32 s100, s100, s1
	s_add_i32 s0, s0, 3
	s_cmp_ge_u32 s0, 5
	s_cselect_b32 s1, 5, 0
	s_sub_i32 s0, s0, s1
	s_cmp_ge_u32 s0, 3
	s_cselect_b32 s1, 0x80, 0
	s_or_b32 s100, s100, s1
	s_cmp_le_u32 s0, 1
	s_cselect_b32 s1, 0x800000, 0
	s_or_b32 s100, s100, s1
	s_add_i32 s0, s0, 3
	s_cmp_ge_u32 s0, 5
	s_cselect_b32 s1, 5, 0
	s_sub_i32 s0, s0, s1
	s_cmp_ge_u32 s0, 3
	s_cselect_b32 s1, 0x100, 0
	s_or_b32 s100, s100, s1
	s_cmp_le_u32 s0, 1
	s_cselect_b32 s1, 0x1000000, 0
	s_or_b32 s100, s100, s1
	s_add_i32 s0, s0, 3
	s_cmp_ge_u32 s0, 5
	s_cselect_b32 s1, 5, 0
	s_sub_i32 s0, s0, s1
	s_cmp_ge_u32 s0, 3
	s_cselect_b32 s1, 0x200, 0
	s_or_b32 s100, s100, s1
	s_cmp_le_u32 s0, 1
	s_cselect_b32 s1, 0x2000000, 0
	s_or_b32 s100, s100, s1
	s_add_i32 s0, s0, 3
	s_cmp_ge_u32 s0, 5
	s_cselect_b32 s1, 5, 0
	s_sub_i32 s0, s0, s1
	s_add_u32 s22, s28, 0x12000000
	s_addc_u32 s23, s29, 0
	s_add_u32 s40, s28, 0xe000000
	s_addc_u32 s41, s29, 0
	s_and_b32 s0, s33, 0xffffffc0
	v_add_u32_e32 v99, s0, v166
	s_mul_i32 s0, s85, 0xcd
	s_lshr_b32 s1, s0, 10
	s_mul_i32 s4, s1, -5
	v_ashrrev_i32_e32 v2, 3, v166
	s_add_i32 s4, s4, s85
	v_lshl_add_u32 v4, s4, 3, v2
	s_add_i32 s4, s0, 0x668
	s_lshr_b32 s4, s4, 10
	s_add_i32 s43, s85, 8
	s_mul_i32 s5, s4, -5
	s_add_i32 s5, s5, s43
	v_lshl_add_u32 v5, s5, 3, v2
	s_add_i32 s5, s0, 0xcd0
	s_lshr_b32 s5, s5, 10
	s_add_i32 s48, s85, 16
	s_mul_i32 s6, s5, -5
	s_add_i32 s6, s6, s48
	v_lshl_add_u32 v6, s6, 3, v2
	s_add_i32 s6, s0, 0x1338
	v_lshrrev_b32_e32 v1, 2, v4
	s_lshr_b32 s6, s6, 10
	v_bfe_u32 v0, v2, 1, 1
	v_and_b32_e32 v3, 7, v166
	v_and_b32_e32 v1, 6, v1
	s_add_i32 s50, s85, 24
	s_mul_i32 s7, s6, -5
	v_bitop3_b32 v1, v1, v3, v0 bitop3:0x36
	s_add_i32 s7, s7, s50
	v_lshlrev_b32_e32 v102, 4, v1
	v_lshrrev_b32_e32 v1, 2, v5
	v_lshl_add_u32 v7, s7, 3, v2
	s_add_i32 s7, s0, 0x19a0
	v_and_b32_e32 v1, 6, v1
	s_lshr_b32 s7, s7, 10
	v_bitop3_b32 v1, v1, v3, v0 bitop3:0x36
	s_add_i32 s54, s85, 32
	s_mul_i32 s8, s7, -5
	v_lshlrev_b32_e32 v106, 4, v1
	v_lshrrev_b32_e32 v1, 2, v6
	s_add_i32 s8, s8, s54
	v_and_b32_e32 v1, 6, v1
	v_lshl_add_u32 v8, s8, 3, v2
	s_add_i32 s8, s0, 0x2008
	v_bitop3_b32 v1, v1, v3, v0 bitop3:0x36
	s_lshr_b32 s8, s8, 10
	v_lshlrev_b32_e32 v110, 4, v1
	v_lshrrev_b32_e32 v1, 2, v7
	s_add_i32 s64, s85, 40
	s_mul_i32 s9, s8, -5
	v_and_b32_e32 v1, 6, v1
	s_add_i32 s9, s9, s64
	v_bitop3_b32 v1, v1, v3, v0 bitop3:0x36
	v_lshl_add_u32 v9, s9, 3, v2
	s_add_i32 s9, s0, 0x2670
	v_lshlrev_b32_e32 v114, 4, v1
	v_lshrrev_b32_e32 v1, 2, v8
	s_lshr_b32 s9, s9, 10
	v_and_b32_e32 v1, 6, v1
	s_add_i32 s66, s85, 48
	s_mul_i32 s10, s9, -5
	v_bitop3_b32 v1, v1, v3, v0 bitop3:0x36
	s_add_i32 s10, s10, s66
	v_lshlrev_b32_e32 v118, 4, v1
	v_lshrrev_b32_e32 v1, 2, v9
	v_lshl_add_u32 v10, s10, 3, v2
	s_add_i32 s10, s0, 0x2cd8
	v_and_b32_e32 v1, 6, v1
	s_lshr_b32 s10, s10, 10
	v_bitop3_b32 v1, v1, v3, v0 bitop3:0x36
	s_add_i32 s68, s85, 56
	s_mul_i32 s11, s10, -5
	v_lshlrev_b32_e32 v122, 4, v1
	v_lshrrev_b32_e32 v1, 2, v10
	s_add_i32 s11, s11, s68
	v_and_b32_e32 v1, 6, v1
	v_lshl_add_u32 v11, s11, 3, v2
	s_add_i32 s11, s0, 0x3340
	v_bitop3_b32 v1, v1, v3, v0 bitop3:0x36
	s_lshr_b32 s11, s11, 10
	v_lshlrev_b32_e32 v126, 4, v1
	v_lshrrev_b32_e32 v1, 2, v11
	s_add_i32 s70, s85, 64
	s_mul_i32 s12, s11, -5
	v_and_b32_e32 v1, 6, v1
	s_add_i32 s12, s12, s70
	s_addk_i32 s0, 0x39a8
	v_bitop3_b32 v1, v1, v3, v0 bitop3:0x36
	v_lshl_add_u32 v12, s12, 3, v2
	s_lshr_b32 s0, s0, 10
	v_lshlrev_b32_e32 v130, 4, v1
	v_lshrrev_b32_e32 v1, 2, v12
	s_add_i32 s72, s85, 0x48
	s_mul_i32 s12, s0, -5
	v_and_b32_e32 v1, 6, v1
	s_add_i32 s12, s12, s72
	v_bitop3_b32 v1, v1, v3, v0 bitop3:0x36
	v_lshl_add_u32 v13, s12, 3, v2
	v_lshlrev_b32_e32 v134, 4, v1
	v_lshrrev_b32_e32 v1, 2, v13
	v_and_b32_e32 v1, 6, v1
	v_bitop3_b32 v0, v1, v3, v0 bitop3:0x36
	v_lshlrev_b32_e32 v138, 4, v0
	v_lshlrev_b32_e32 v0, 3, v169
; template <int KIND> __device__ __forceinline__ void attn_dma(unsigned dst, const bf16_t* src, const AttnUnit& u, int wid, int lane) {
;     ...
;             const int w = (pi * 205) >> 10, p = pi - 5 * w, c = 8 * p + (lane >> 3);
;             const int sw = (KIND == 0) ? (((c >> 1) & 1) | (((c >> 3) & 3) << 1)) : ((((c >> 1) & 1) << 1) | (((c >> 3) & 1) << 2));
;             const int ch = (lane & 7) ^ sw;
;             const char* gp = base + (w * 64 + c) * (HD * 2) + ch * 16;
;             glds16(gp, (unsigned)__builtin_amdgcn_readfirstlane(dst + pi * 1024));
; __device__ __forceinline__ void p2_attention(Frame& F, const bf16_t* Qg, const bf16_t* Kg, const bf16_t* Vg, bf16_t* MIX) {
;     ...
;                 const int o = 8 * jb, kcol0 = 24 * u.jh + o, cq = 32 * u.jh + 16 * jb + q;
;                 int cs = cq - 8; cs = cs < 0 ? 0 : cs; cs = cs > 48 ? 48 : cs;
;                 f32x4 sc[8][2];
;                 {
;                     const int fk = ((q >> 1) & 1) | (((jb + (q >> 2)) & 3) << 1), x0 = g ^ fk;
;                     const LAS unsigned char* ka = lds + AT_A + (wbase * 40 + o + 8 * (q >> 2) + (q & 3)) * 128;
;                     const LAS unsigned char* k0p = ka + x0 * 16;
;                     const LAS unsigned char* k1p = ka + (x0 ^ 4) * 16;
; #pragma unroll
;                     for (int wl = 0; wl < 8; ++wl)
; #pragma unroll
;                         for (int blk = 0; blk < 2; ++blk) {
;                             const bf16x8 k0 = *(const LAS bf16x8*)(k0p + wl * 5120 + blk * 512), k1 = *(const LAS bf16x8*)(k1p + wl * 5120 + blk * 512);
;                             f32x4 a = (f32x4){0.f, 0.f, 0.f, 0.f};
;                             a = __builtin_amdgcn_mfma_f32_16x16x32_bf16(k0, qf[jb][0], a, 0, 0, 0);
;                             a = __builtin_amdgcn_mfma_f32_16x16x32_bf16(k1, qf[jb][1], a, 0, 0, 0);
;                             sc[wl][blk] = a;
;                         }
;                 }
;                 const LAS float* tab = (const LAS float*)(lds + AT_TAB) + (rs - r + 7) * 64 + 16 + (kcol0 - cq + 15) + 8 * g;
;                 const int voff = kcol0 + 8 * g - cs;
;                 float mx = -INFINITY;
; #pragma unroll
;                 for (int wl = 0; wl < 8; ++wl)
; #pragma unroll
;                     for (int blk = 0; blk < 2; ++blk)
; #pragma unroll
;                         for (int e = 0; e < 4; ++e) {
	v_ashrrev_i32_e32 v1, 31, v0
	v_lshl_add_u64 v[140:141], v[0:1], 1, s[36:37]
	v_and_b32_e32 v1, 2, v2
	v_lshrrev_b32_e32 v2, 1, v4
	v_and_b32_e32 v2, 4, v2
	v_bitop3_b32 v2, v2, v3, v1 bitop3:0x36
	v_lshlrev_b32_e32 v142, 4, v2
	v_lshrrev_b32_e32 v2, 1, v5
	v_and_b32_e32 v2, 4, v2
	v_bitop3_b32 v2, v2, v3, v1 bitop3:0x36
	v_lshlrev_b32_e32 v144, 4, v2
	v_lshrrev_b32_e32 v2, 1, v6
	v_and_b32_e32 v2, 4, v2
	v_bitop3_b32 v2, v2, v3, v1 bitop3:0x36
	v_lshlrev_b32_e32 v146, 4, v2
	v_lshrrev_b32_e32 v2, 1, v7
	v_and_b32_e32 v2, 4, v2
	v_bitop3_b32 v2, v2, v3, v1 bitop3:0x36
	v_lshlrev_b32_e32 v148, 4, v2
	v_lshrrev_b32_e32 v2, 1, v8
	v_and_b32_e32 v2, 4, v2
	v_bitop3_b32 v2, v2, v3, v1 bitop3:0x36
	v_lshlrev_b32_e32 v150, 4, v2
	v_lshrrev_b32_e32 v2, 1, v9
	v_and_b32_e32 v2, 4, v2
	v_bitop3_b32 v2, v2, v3, v1 bitop3:0x36
	v_lshlrev_b32_e32 v152, 4, v2
	v_lshrrev_b32_e32 v2, 1, v10
	v_and_b32_e32 v2, 4, v2
	v_bitop3_b32 v2, v2, v3, v1 bitop3:0x36
	v_lshlrev_b32_e32 v154, 4, v2
	v_lshrrev_b32_e32 v2, 1, v11
	v_and_b32_e32 v2, 4, v2
	v_bitop3_b32 v2, v2, v3, v1 bitop3:0x36
	v_lshlrev_b32_e32 v156, 4, v2
	v_lshrrev_b32_e32 v2, 1, v12
	v_and_b32_e32 v2, 4, v2
	v_bitop3_b32 v2, v2, v3, v1 bitop3:0x36
	v_lshlrev_b32_e32 v158, 4, v2
	v_lshrrev_b32_e32 v2, 1, v13
	v_and_b32_e32 v2, 4, v2
	v_bitop3_b32 v1, v2, v3, v1 bitop3:0x36
	s_lshl_b32 s4, s4, 13
	v_lshlrev_b32_e32 v160, 4, v1
	v_bfe_u32 v164, v166, 2, 2
	v_and_b32_e32 v1, 3, v166
	v_add_u32_e32 v170, 8, v0
	v_lshrrev_b32_e32 v0, 2, v166
	v_lshl_add_u32 v104, v5, 7, s4
	s_lshl_b32 s5, s5, 13
	s_add_i32 s12, 0, 0x12c00
	v_lshl_or_b32 v165, v164, 3, v1
	v_and_b32_e32 v5, 2, v0
	v_and_b32_e32 v0, 16, v96
	v_and_b32_e32 v1, 8, v96
	v_lshl_add_u32 v108, v6, 7, s5
	v_add3_u32 v6, s12, v0, v1
	v_lshlrev_b32_e32 v0, 6, v166
	v_mov_b32_e32 v97, 0
	v_and_b32_e32 v96, 0x3c0, v0
	v_and_b32_e32 v2, -16, v166
	s_lshl_b32 s1, s1, 13
	v_lshl_add_u64 v[0:1], s[24:25], 0, v[96:97]
	v_ashrrev_i32_e32 v3, 31, v2
	v_lshl_add_u32 v100, v4, 7, s1
	v_bfe_u32 v4, v166, 1, 1
	v_lshl_add_u64 v[162:163], v[0:1], 0, v[2:3]
	v_lshlrev_b32_e32 v0, 1, v164
	v_bitop3_b32 v1, v0, v169, v4 bitop3:0x36
	v_add_u32_e32 v0, 2, v0
	v_and_b32_e32 v0, 6, v0
	v_bitop3_b32 v0, v0, v169, v4 bitop3:0x36
	v_lshlrev_b32_e32 v173, 4, v0
	v_lshlrev_b32_e32 v0, 2, v169
	v_and_or_b32 v0, v0, 4, v5
	v_lshlrev_b32_e32 v176, 4, v0
	v_add_u32_e32 v0, 1, v169
	v_lshlrev_b32_e32 v171, 4, v1
	v_lshlrev_b32_e32 v1, 2, v0
	v_and_or_b32 v1, v1, 4, v5
	v_and_b32_e32 v185, 63, v166
	s_lshl_b32 s4, s43, 10
	s_lshl_b32 s5, s48, 10
	v_lshl_add_u32 v180, v0, 10, v6
	v_lshlrev_b32_e32 v181, 4, v1
	v_add_u32_e32 v0, -16, v185
	v_and_b32_e32 v1, 64, v168
	s_add_i32 s45, s4, 0
	s_add_i32 s49, s5, 0
	s_lshl_b32 s0, s0, 13
	s_add_i32 s37, s4, s12
	s_add_i32 s74, s5, s12
	v_cmp_gt_u32_e64 s[4:5], 31, v0
	v_xor_b32_e32 v0, 16, v168
	v_add_u32_e32 v1, 64, v1
	v_lshl_add_u32 v136, v13, 7, s0
	s_lshl_b32 s0, s72, 10
	v_cmp_lt_i32_e32 vcc, v0, v1
	s_lshl_b32 s1, s85, 10
	s_add_i32 s73, s0, 0
	s_add_i32 s81, s0, s12
	s_movk_i32 s0, 0x3c0
	v_cndmask_b32_e32 v0, v168, v0, vcc
	s_add_i32 s42, s1, 0
	s_add_i32 s36, s1, s12
	v_cmp_gt_i32_e64 s[20:21], s0, v99
	v_lshlrev_b32_e32 v186, 2, v0
	v_xor_b32_e32 v0, 32, v168
	s_add_i32 s0, 0, 0x25800
	s_lshl_b32 s1, s85, 8
	s_lshl_b32 s6, s6, 13
	s_lshl_b32 s7, s7, 13
	s_lshl_b32 s8, s8, 13
	s_lshl_b32 s9, s9, 13
	s_lshl_b32 s10, s10, 13
	s_lshl_b32 s11, s11, 13
	v_lshl_add_u32 v175, v169, 10, v6
	v_cmp_lt_i32_e32 vcc, v0, v1
	v_lshl_add_u32 v169, v169, 5, s0
	s_add_i32 s0, s0, s1
	v_and_b32_e32 v98, 15, v166
	v_lshl_add_u32 v112, v7, 7, s6
	s_lshl_b32 s6, s50, 10
	v_lshl_add_u32 v116, v8, 7, s7
	s_lshl_b32 s7, s54, 10
	v_lshl_add_u32 v120, v9, 7, s8
	s_lshl_b32 s8, s64, 10
	v_lshl_add_u32 v124, v10, 7, s9
	s_lshl_b32 s9, s66, 10
	v_lshl_add_u32 v128, v11, 7, s10
	s_lshl_b32 s10, s68, 10
	v_lshl_add_u32 v132, v12, 7, s11
	s_lshl_b32 s11, s70, 10
	v_cndmask_b32_e32 v0, v168, v0, vcc
	v_lshl_add_u32 v166, v166, 2, s0
	s_lshl_b32 s0, s86, 5
	v_ashrrev_i32_e32 v101, 31, v100
	v_mov_b32_e32 v103, v97
	v_ashrrev_i32_e32 v105, 31, v104
	v_mov_b32_e32 v107, v97
	v_ashrrev_i32_e32 v109, 31, v108
	v_mov_b32_e32 v111, v97
	v_ashrrev_i32_e32 v113, 31, v112
	v_mov_b32_e32 v115, v97
	s_add_i32 s51, s6, 0
	v_ashrrev_i32_e32 v117, 31, v116
	v_mov_b32_e32 v119, v97
	s_add_i32 s55, s7, 0
	v_ashrrev_i32_e32 v121, 31, v120
	v_mov_b32_e32 v123, v97
	s_add_i32 s65, s8, 0
	v_ashrrev_i32_e32 v125, 31, v124
	v_mov_b32_e32 v127, v97
	s_add_i32 s67, s9, 0
	v_ashrrev_i32_e32 v129, 31, v128
	v_mov_b32_e32 v131, v97
	s_add_i32 s69, s10, 0
	v_ashrrev_i32_e32 v133, 31, v132
	v_mov_b32_e32 v135, v97
	s_add_i32 s71, s11, 0
	v_ashrrev_i32_e32 v137, 31, v136
	v_mov_b32_e32 v139, v97
	v_mov_b32_e32 v143, v97
	v_mov_b32_e32 v145, v97
	v_mov_b32_e32 v147, v97
	v_mov_b32_e32 v149, v97
	s_add_i32 s75, s6, s12
	v_mov_b32_e32 v151, v97
	s_add_i32 s76, s7, s12
	v_mov_b32_e32 v153, v97
	s_add_i32 s77, s8, s12
	v_mov_b32_e32 v155, v97
	s_add_i32 s78, s9, s12
	v_mov_b32_e32 v157, v97
	s_add_i32 s79, s10, s12
	v_mov_b32_e32 v159, v97
	s_add_i32 s80, s11, s12
	v_mov_b32_e32 v161, v97
	v_xor_b32_e32 v172, 64, v171
	v_xor_b32_e32 v174, 64, v173
	v_xor_b32_e32 v177, 32, v176
	v_xor_b32_e32 v178, 64, v176
	v_xor_b32_e32 v179, 0x60, v176
	v_xor_b32_e32 v182, 32, v181
	v_xor_b32_e32 v183, 64, v181
	v_xor_b32_e32 v184, 0x60, v181
	s_lshl_b32 s82, s3, 3
	v_lshlrev_b32_e32 v168, 2, v0
	s_or_b32 s83, s0, 4
	s_lshl_b32 s86, s3, 5
	s_movk_i32 s87, 0x1bf
	s_mov_b32 s88, 0xff800000
	v_mov_b32_e32 v187, 0xff800000
	s_branch .LBB0_266
